# unorm_chunk wave sums via DPP adds and permlane swaps instead of six ds_bpermute round trips
# speedup vs baseline: 1.0146x; 1.0083x over previous
; __device__ __forceinline__ unsigned cvt_pk_bf16(float lo, float hi) { unsigned r; asm volatile("v_cvt_pk_bf16_f32 %0, %1, %2" : "=v"(r) : "v"(lo), "v"(hi)); return r; }
; __device__ __forceinline__ float shx(float v, int lane, int mask) { return __builtin_bit_cast(float, __builtin_amdgcn_ds_bpermute((lane ^ mask) << 2, __builtin_bit_cast(int, v))); }
; #define LAS __attribute__((address_space(3)))
; __device__ __forceinline__ float wsum_l(float v, int lane) {
; #pragma unroll
;     for (int o = 1; o < 64; o <<= 1) v += pg8::shx(v, lane, o);
;     return v;
; template <bool F32SRC> __device__ __forceinline__ void unorm_chunk(LAS unsigned char* lds, const float* xsrc, bf16_t* hbio, bf16_t* Ug, int chunk, const int tid) {
;     ...
;         } else { const u32x4* xr = (const u32x4*)(hbio + row * DM) + lane; u32x4 w[2]; float v[16]; float ss = 0.f;
; #pragma unroll
;             for (int j = 0; j < 2; ++j) { w[j] = xr[64 * j];
;                 v[8 * j + 0] = __uint_as_float(w[j].x << 16); v[8 * j + 1] = __uint_as_float(w[j].x & 0xffff0000u); v[8 * j + 2] = __uint_as_float(w[j].y << 16); v[8 * j + 3] = __uint_as_float(w[j].y & 0xffff0000u);
;                 v[8 * j + 4] = __uint_as_float(w[j].z << 16); v[8 * j + 5] = __uint_as_float(w[j].z & 0xffff0000u); v[8 * j + 6] = __uint_as_float(w[j].w << 16); v[8 * j + 7] = __uint_as_float(w[j].w & 0xffff0000u); }
; #pragma unroll
;             for (int i = 0; i < 16; ++i) ss += v[i] * v[i];
;             const float rstd = rsqrtf(wsum_l(ss, lane) * (1.0f / DM) + EPS);
; #pragma unroll
;             for (int j = 0; j < 2; ++j) { u32x4 q; q.x = pg8::cvt_pk_bf16(v[8 * j] * rstd, v[8 * j + 1] * rstd); q.y = pg8::cvt_pk_bf16(v[8 * j + 2] * rstd, v[8 * j + 3] * rstd);
;                 q.z = pg8::cvt_pk_bf16(v[8 * j + 4] * rstd, v[8 * j + 5] * rstd); q.w = pg8::cvt_pk_bf16(v[8 * j + 6] * rstd, v[8 * j + 7] * rstd); *(LAS u32x4*)(T + s * 2080 + (64 * j + lane) * 16) = q; } }
.LBB0_307:
	v_readfirstlane_b32 s0, v66
	s_ashr_i32 s1, s0, 6
	s_lshl_b32 s0, s1, 1
	s_mul_i32 s3, s1, 0x1040
	v_lshl_or_b32 v14, s1, 3, v11
	s_ashr_i32 s1, s0, 31
	s_lshl_b64 s[10:11], s[0:1], 11
	s_add_u32 s10, s24, s10
	v_ashrrev_i32_e32 v15, 31, v14
	s_addc_u32 s11, s25, s11
	v_lshl_add_u32 v38, v14, 5, v12
	v_or_b32_e32 v26, 2, v14
	v_or_b32_e32 v28, 4, v14
	v_or_b32_e32 v30, 6, v14
	v_lshlrev_b64 v[32:33], 19, v[14:15]
	v_lshl_add_u64 v[14:15], s[10:11], 0, v[2:3]
	v_add_co_u32_e32 v22, vcc, s18, v14
	v_add_u32_e32 v13, s3, v10
	s_nop 0
	v_addc_co_u32_e32 v23, vcc, 0, v15, vcc
	global_load_dwordx4 v[14:17], v[22:23], off
	global_load_dwordx4 v[18:21], v[22:23], off offset:1024
	global_load_dwordx4 v[140:143], v[22:23], off offset:2048
	global_load_dwordx4 v[144:147], v[22:23], off offset:3072
	s_or_b32 s0, s0, 1
	s_mulk_i32 s0, 0x820
	v_lshl_add_u64 v[32:33], v[0:1], 0, v[32:33]
	v_lshl_add_u64 v[32:33], s[24:25], 0, v[32:33]
	s_add_i32 s2, s2, s12
	v_lshl_add_u64 v[2:3], v[2:3], 0, s[16:17]
	s_cmpk_lt_i32 s2, 0x400
	s_waitcnt vmcnt(0)
	v_and_b32_e32 v25, 0xffff0000, v14
	v_lshlrev_b32_e32 v24, 16, v14
	v_mul_f32_e32 v42, v25, v25
	v_lshlrev_b32_e32 v27, 16, v15
	v_fmac_f32_e32 v42, v24, v24
	v_and_b32_e32 v29, 0xffff0000, v15
	v_fmac_f32_e32 v42, v27, v27
	v_lshlrev_b32_e32 v31, 16, v16
	v_fmac_f32_e32 v42, v29, v29
	v_and_b32_e32 v34, 0xffff0000, v16
	v_fmac_f32_e32 v42, v31, v31
	v_lshlrev_b32_e32 v35, 16, v17
	v_fmac_f32_e32 v42, v34, v34
	v_and_b32_e32 v36, 0xffff0000, v17
	v_fmac_f32_e32 v42, v35, v35
	s_waitcnt vmcnt(0)
	v_lshlrev_b32_e32 v37, 16, v18
	v_fmac_f32_e32 v42, v36, v36
	v_and_b32_e32 v39, 0xffff0000, v18
	v_fmac_f32_e32 v42, v37, v37
	v_lshlrev_b32_e32 v40, 16, v19
	v_fmac_f32_e32 v42, v39, v39
	v_and_b32_e32 v41, 0xffff0000, v19
	v_and_b32_e32 v14, 0xffff0000, v20
	v_lshlrev_b32_e32 v15, 16, v20
	v_fmac_f32_e32 v42, v40, v40
	v_pk_mul_f32 v[18:19], v[14:15], v[14:15]
	v_fmac_f32_e32 v42, v41, v41
	v_and_b32_e32 v16, 0xffff0000, v21
	v_lshlrev_b32_e32 v17, 16, v21
	v_add_f32_e32 v19, v19, v42
	v_pk_mul_f32 v[20:21], v[16:17], v[16:17]
	v_add_f32_e32 v18, v18, v19
	v_add_f32_e32 v18, v21, v18
	v_add_f32_e32 v18, v20, v18
	s_nop 1
	v_add_f32_dpp v18, v18, v18 quad_perm:[1,0,3,2] row_mask:0xf bank_mask:0xf
	s_nop 1
	v_add_f32_dpp v18, v18, v18 quad_perm:[2,3,0,1] row_mask:0xf bank_mask:0xf
	s_nop 1
	v_add_f32_dpp v18, v18, v18 row_half_mirror row_mask:0xf bank_mask:0xf
	s_nop 1
	v_add_f32_dpp v18, v18, v18 row_mirror row_mask:0xf bank_mask:0xf
	v_mov_b32_e32 v19, v18
	s_nop 1
	v_permlane16_swap_b32_e32 v19, v18
	s_nop 1
	v_add_f32_e32 v18, v18, v19
	v_mov_b32_e32 v19, v18
	s_nop 1
	v_permlane32_swap_b32_e32 v19, v18
	s_nop 1
	v_add_f32_e32 v18, v18, v19
	v_fmamk_f32 v18, v18, 0x3a800000, v226
	v_mul_f32_e32 v19, 0x4b800000, v18
	v_cmp_gt_f32_e32 vcc, s5, v18
	s_nop 1
	v_cndmask_b32_e32 v18, v18, v19, vcc
	v_rsq_f32_e32 v18, v18
	s_nop 0
	v_mul_f32_e32 v19, 0x45800000, v18
	v_cndmask_b32_e32 v18, v18, v19, vcc
	v_mul_f32_e32 v19, v18, v24
	v_mul_f32_e32 v20, v18, v25
	v_mul_f32_e32 v21, v18, v27
	v_mul_f32_e32 v24, v18, v29
	v_mul_f32_e32 v25, v18, v31
	v_mul_f32_e32 v27, v18, v34
	v_mul_f32_e32 v29, v18, v35
	v_mul_f32_e32 v31, v18, v36
	v_mul_f32_e32 v34, v18, v37
	v_mul_f32_e32 v35, v18, v39
	v_mul_f32_e32 v36, v18, v40
	v_mul_f32_e32 v37, v18, v41
	v_mul_f32_e32 v39, v18, v15
	v_mul_f32_e32 v40, v18, v14
	v_mul_f32_e32 v41, v18, v17
	v_mul_f32_e32 v18, v18, v16
	v_cvt_pk_bf16_f32 v14, v19, v20
	v_cvt_pk_bf16_f32 v15, v21, v24
	v_cvt_pk_bf16_f32 v16, v25, v27
	v_cvt_pk_bf16_f32 v17, v29, v31
	ds_write_b128 v13, v[14:17]
	v_cvt_pk_bf16_f32 v14, v34, v35
	v_cvt_pk_bf16_f32 v15, v36, v37
	v_cvt_pk_bf16_f32 v16, v39, v40
	v_cvt_pk_bf16_f32 v17, v41, v18
	v_mov_b32_e32 v18, v140
	v_mov_b32_e32 v19, v141
	v_mov_b32_e32 v20, v142
	v_mov_b32_e32 v21, v143
	v_mov_b32_e32 v22, v144
	v_mov_b32_e32 v23, v145
	v_mov_b32_e32 v24, v146
	v_mov_b32_e32 v25, v147
	v_ashrrev_i32_e32 v27, 31, v26
	v_lshl_add_u32 v39, v26, 5, v12
	v_lshlrev_b64 v[26:27], 19, v[26:27]
	v_ashrrev_i32_e32 v29, 31, v28
	v_lshl_add_u64 v[26:27], v[0:1], 0, v[26:27]
	v_lshl_add_u32 v40, v28, 5, v12
	v_lshlrev_b64 v[28:29], 19, v[28:29]
	v_lshl_add_u64 v[34:35], s[24:25], 0, v[26:27]
	v_lshl_add_u64 v[28:29], v[0:1], 0, v[28:29]
	ds_write_b128 v13, v[14:17] offset:1024
	v_lshl_add_u64 v[36:37], s[24:25], 0, v[28:29]
	v_add_u32_e32 v26, s0, v10
	v_lshl_add_u32 v41, v30, 5, v12
	v_ashrrev_i32_e32 v31, 31, v30
	v_lshlrev_b64 v[30:31], 19, v[30:31]
	v_lshl_add_u64 v[30:31], v[0:1], 0, v[30:31]
	v_lshl_add_u64 v[30:31], s[24:25], 0, v[30:31]
	v_lshl_add_u64 v[0:1], v[0:1], 0, s[14:15]
	s_waitcnt vmcnt(1)
; __device__ __forceinline__ unsigned cvt_pk_bf16(float lo, float hi) { unsigned r; asm volatile("v_cvt_pk_bf16_f32 %0, %1, %2" : "=v"(r) : "v"(lo), "v"(hi)); return r; }
; #define LAS __attribute__((address_space(3)))
; #define LDS_WAIT() asm volatile("s_waitcnt lgkmcnt(0)" ::: "memory")
; template <bool F32SRC> __device__ __forceinline__ void unorm_chunk(LAS unsigned char* lds, const float* xsrc, bf16_t* hbio, bf16_t* Ug, int chunk, const int tid) {
;     ...
;         } else { const u32x4* xr = (const u32x4*)(hbio + row * DM) + lane; u32x4 w[2]; float v[16]; float ss = 0.f;
; #pragma unroll
;             for (int j = 0; j < 2; ++j) { w[j] = xr[64 * j];
;                 v[8 * j + 0] = __uint_as_float(w[j].x << 16); v[8 * j + 1] = __uint_as_float(w[j].x & 0xffff0000u); v[8 * j + 2] = __uint_as_float(w[j].y << 16); v[8 * j + 3] = __uint_as_float(w[j].y & 0xffff0000u);
;                 v[8 * j + 4] = __uint_as_float(w[j].z << 16); v[8 * j + 5] = __uint_as_float(w[j].z & 0xffff0000u); v[8 * j + 6] = __uint_as_float(w[j].w << 16); v[8 * j + 7] = __uint_as_float(w[j].w & 0xffff0000u); }
; #pragma unroll
;             for (int i = 0; i < 16; ++i) ss += v[i] * v[i];
;             const float rstd = rsqrtf(wsum_l(ss, lane) * (1.0f / DM) + EPS);
; #pragma unroll
;             for (int j = 0; j < 2; ++j) { u32x4 q; q.x = pg8::cvt_pk_bf16(v[8 * j] * rstd, v[8 * j + 1] * rstd); q.y = pg8::cvt_pk_bf16(v[8 * j + 2] * rstd, v[8 * j + 3] * rstd);
;                 q.z = pg8::cvt_pk_bf16(v[8 * j + 4] * rstd, v[8 * j + 5] * rstd); q.w = pg8::cvt_pk_bf16(v[8 * j + 6] * rstd, v[8 * j + 7] * rstd); *(LAS u32x4*)(T + s * 2080 + (64 * j + lane) * 16) = q; } }
;     }
;     LDS_WAIT(); __syncthreads();
; #pragma unroll
;     for (int i = 0; i < 4; ++i) { const int gq = 8 * wid + 2 * i + (lane >> 5), l = lane & 31, s = l >> 1, hf = l & 1;
;         const u32x4 q = *(const LAS u32x4*)(T + s * 2080 + gq * 32 + hf * 16);
;         *(u32x4*)(Ug + ((size_t)gq * 1024 + chunk) * 256 + l * 8) = q; }
;     LDS_WAIT(); __syncthreads();
	v_and_b32_e32 v27, 0xffff0000, v18
	v_lshlrev_b32_e32 v13, 16, v18
	s_waitcnt vmcnt(0)
	v_and_b32_e32 v14, 0xffff0000, v24
	v_lshlrev_b32_e32 v15, 16, v24
	v_mul_f32_e32 v24, v27, v27
	v_lshlrev_b32_e32 v28, 16, v19
	v_fmac_f32_e32 v24, v13, v13
	v_and_b32_e32 v29, 0xffff0000, v19
	v_fmac_f32_e32 v24, v28, v28
	v_lshlrev_b32_e32 v42, 16, v20
	v_fmac_f32_e32 v24, v29, v29
	v_and_b32_e32 v43, 0xffff0000, v20
	v_fmac_f32_e32 v24, v42, v42
	v_lshlrev_b32_e32 v44, 16, v21
	v_fmac_f32_e32 v24, v43, v43
	v_and_b32_e32 v45, 0xffff0000, v21
	v_fmac_f32_e32 v24, v44, v44
	v_lshlrev_b32_e32 v46, 16, v22
	v_fmac_f32_e32 v24, v45, v45
	v_and_b32_e32 v22, 0xffff0000, v22
	v_fmac_f32_e32 v24, v46, v46
	v_lshlrev_b32_e32 v47, 16, v23
	v_fmac_f32_e32 v24, v22, v22
	v_and_b32_e32 v23, 0xffff0000, v23
	v_fmac_f32_e32 v24, v47, v47
	v_pk_mul_f32 v[18:19], v[14:15], v[14:15]
	v_fmac_f32_e32 v24, v23, v23
	v_and_b32_e32 v16, 0xffff0000, v25
	v_lshlrev_b32_e32 v17, 16, v25
	v_add_f32_e32 v19, v19, v24
	v_pk_mul_f32 v[20:21], v[16:17], v[16:17]
	v_add_f32_e32 v18, v18, v19
	v_add_f32_e32 v18, v21, v18
	v_add_f32_e32 v18, v20, v18
	s_nop 1
	v_add_f32_dpp v18, v18, v18 quad_perm:[1,0,3,2] row_mask:0xf bank_mask:0xf
	s_nop 1
	v_add_f32_dpp v18, v18, v18 quad_perm:[2,3,0,1] row_mask:0xf bank_mask:0xf
	s_nop 1
	v_add_f32_dpp v18, v18, v18 row_half_mirror row_mask:0xf bank_mask:0xf
	s_nop 1
	v_add_f32_dpp v18, v18, v18 row_mirror row_mask:0xf bank_mask:0xf
	v_mov_b32_e32 v19, v18
	s_nop 1
	v_permlane16_swap_b32_e32 v19, v18
	s_nop 1
	v_add_f32_e32 v18, v18, v19
	v_mov_b32_e32 v19, v18
	s_nop 1
	v_permlane32_swap_b32_e32 v19, v18
	s_nop 1
	v_add_f32_e32 v18, v18, v19
	v_fmamk_f32 v18, v18, 0x3a800000, v226
	v_mul_f32_e32 v19, 0x4b800000, v18
	v_cmp_gt_f32_e32 vcc, s5, v18
	s_nop 1
	v_cndmask_b32_e32 v18, v18, v19, vcc
	v_rsq_f32_e32 v18, v18
	s_nop 0
	v_mul_f32_e32 v19, 0x45800000, v18
	v_cndmask_b32_e32 v18, v18, v19, vcc
	v_mul_f32_e32 v13, v18, v13
	v_mul_f32_e32 v19, v18, v27
	v_mul_f32_e32 v20, v18, v28
	v_mul_f32_e32 v21, v18, v29
	v_mul_f32_e32 v24, v18, v42
	v_mul_f32_e32 v25, v18, v43
	v_mul_f32_e32 v27, v18, v44
	v_mul_f32_e32 v28, v18, v45
	v_mul_f32_e32 v29, v18, v46
	v_mul_f32_e32 v22, v18, v22
	v_mul_f32_e32 v42, v18, v47
	v_mul_f32_e32 v23, v18, v23
	v_mul_f32_e32 v43, v18, v15
	v_mul_f32_e32 v44, v18, v14
	v_mul_f32_e32 v45, v18, v17
	v_mul_f32_e32 v18, v18, v16
	v_cvt_pk_bf16_f32 v14, v13, v19
	v_cvt_pk_bf16_f32 v15, v20, v21
	v_cvt_pk_bf16_f32 v16, v24, v25
	v_cvt_pk_bf16_f32 v17, v27, v28
	ds_write_b128 v26, v[14:17]
	v_cvt_pk_bf16_f32 v14, v29, v22
	v_cvt_pk_bf16_f32 v15, v42, v23
	v_cvt_pk_bf16_f32 v16, v43, v44
	v_cvt_pk_bf16_f32 v17, v45, v18
	ds_write_b128 v26, v[14:17] offset:1024
	s_waitcnt lgkmcnt(0)
	s_waitcnt lgkmcnt(0)
	s_barrier
	ds_read_b128 v[14:17], v38
	ds_read_b128 v[18:21], v39
	ds_read_b128 v[22:25], v40
	ds_read_b128 v[26:29], v41
	s_waitcnt lgkmcnt(3)
	global_store_dwordx4 v[32:33], v[14:17], off
	s_waitcnt lgkmcnt(2)
	global_store_dwordx4 v[34:35], v[18:21], off
	s_waitcnt lgkmcnt(1)
	global_store_dwordx4 v[36:37], v[22:25], off
	s_waitcnt lgkmcnt(0)
	global_store_dwordx4 v[30:31], v[26:29], off
	s_waitcnt lgkmcnt(0)
	s_barrier
	s_cbranch_scc1 .LBB0_307

; __device__ __forceinline__ unsigned cvt_pk_bf16(float lo, float hi) { unsigned r; asm volatile("v_cvt_pk_bf16_f32 %0, %1, %2" : "=v"(r) : "v"(lo), "v"(hi)); return r; }
; __device__ __forceinline__ float shx(float v, int lane, int mask) { return __builtin_bit_cast(float, __builtin_amdgcn_ds_bpermute((lane ^ mask) << 2, __builtin_bit_cast(int, v))); }
; #define LAS __attribute__((address_space(3)))
; __device__ __forceinline__ float wsum_l(float v, int lane) {
; #pragma unroll
;     for (int o = 1; o < 64; o <<= 1) v += pg8::shx(v, lane, o);
;     return v;
; template <bool F32SRC> __device__ __forceinline__ void unorm_chunk(LAS unsigned char* lds, const float* xsrc, bf16_t* hbio, bf16_t* Ug, int chunk, const int tid) {
;     ...
;     for (int rr = 0; rr < 2; ++rr) { const int s = 2 * wid + rr; const size_t row = (size_t)chunk * 16 + s;
;         if (F32SRC) { const f32x4* xr = (const f32x4*)(xsrc + row * DM) + lane; f32x4 v[4]; float ss = 0.f;
; #pragma unroll
;             for (int j = 0; j < 4; ++j) { v[j] = __builtin_nontemporal_load(xr + 64 * j); ss += (v[j].x * v[j].x + v[j].y * v[j].y) + (v[j].z * v[j].z + v[j].w * v[j].w); }
;             const float rstd = rsqrtf(wsum_l(ss, lane) * (1.0f / DM) + EPS);
;             u32x2* o = (u32x2*)(hbio + row * DM) + lane;
; #pragma unroll
;             for (int j = 0; j < 4; ++j) { u32x2 w; w.x = pg8::cvt_pk_bf16(v[j].x, v[j].y); w.y = pg8::cvt_pk_bf16(v[j].z, v[j].w); o[64 * j] = w;
;                 u32x2 q; q.x = pg8::cvt_pk_bf16(v[j].x * rstd, v[j].y * rstd); q.y = pg8::cvt_pk_bf16(v[j].z * rstd, v[j].w * rstd); *(LAS u32x2*)(T + s * 2080 + (64 * j + lane) * 8) = q; }
.LBB0_312:
	ds_read_b64 v[6:7], v236
	ds_read_b64 v[8:9], v236
	v_readfirstlane_b32 s0, v66
	s_ashr_i32 s1, s0, 6
	s_lshl_b32 s0, s1, 1
	s_mul_i32 s3, s1, 0x1040
	s_mov_b32 s2, s97
	v_lshl_or_b32 v20, s1, 3, v16
	s_ashr_i32 s1, s0, 31
	v_add_u32_e32 v19, s3, v18
	s_waitcnt lgkmcnt(0)
	v_readfirstlane_b32 s3, v7
	s_waitcnt lgkmcnt(0)
	v_readfirstlane_b32 s96, v8
	s_lshl_b64 s[10:11], s[0:1], 12
	s_or_b64 s[2:3], s[96:97], s[2:3]
	s_add_u32 s2, s2, s10
	v_ashrrev_i32_e32 v21, 31, v20
	v_or_b32_e32 v22, 2, v20
	s_addc_u32 s3, s3, s11
	v_lshl_add_u32 v60, v20, 5, v17
	v_or_b32_e32 v32, 4, v20
	v_or_b32_e32 v34, 6, v20
	v_lshlrev_b64 v[20:21], 19, v[20:21]
	v_ashrrev_i32_e32 v23, 31, v22
	v_lshl_add_u64 v[40:41], s[2:3], 0, v[2:3]
	v_lshl_add_u32 v61, v22, 5, v17
	v_lshl_add_u64 v[36:37], v[0:1], 0, v[20:21]
	v_lshlrev_b64 v[38:39], 19, v[22:23]
	global_load_dwordx4 v[6:9], v[40:41], off nt
	global_load_dwordx4 v[20:23], v[40:41], off offset:1024 nt
	global_load_dwordx4 v[24:27], v[40:41], off offset:3072 nt
	global_load_dwordx4 v[28:31], v[40:41], off offset:2048 nt
	s_lshl_b64 s[10:11], s[0:1], 11
	s_add_u32 s2, s38, s10
	s_addc_u32 s3, s39, s11
	v_add_co_u32_e32 v40, vcc, s13, v40
	v_lshl_add_u64 v[42:43], s[2:3], 0, v[4:5]
	s_nop 0
	v_addc_co_u32_e32 v41, vcc, 0, v41, vcc
	s_nop 0
	global_load_dwordx4 v[140:143], v[40:41], off nt
	global_load_dwordx4 v[144:147], v[40:41], off offset:1024 nt
	global_load_dwordx4 v[148:151], v[40:41], off offset:2048 nt
	global_load_dwordx4 v[152:155], v[40:41], off offset:3072 nt
	v_add_co_u32_e32 v42, vcc, s21, v42
	s_or_b32 s0, s0, 1
	s_nop 0
	v_addc_co_u32_e32 v43, vcc, 0, v43, vcc
	s_mulk_i32 s0, 0x820
	v_lshl_add_u32 v62, v32, 5, v17
	v_lshl_add_u32 v63, v34, 5, v17
	v_ashrrev_i32_e32 v33, 31, v32
	v_ashrrev_i32_e32 v35, 31, v34
	v_lshlrev_b64 v[32:33], 19, v[32:33]
	v_lshlrev_b64 v[34:35], 19, v[34:35]
	v_lshl_add_u64 v[36:37], s[38:39], 0, v[36:37]
	v_lshl_add_u64 v[38:39], v[0:1], 0, v[38:39]
	v_lshl_add_u64 v[32:33], v[0:1], 0, v[32:33]
	v_lshl_add_u64 v[34:35], v[0:1], 0, v[34:35]
	v_lshl_add_u64 v[38:39], s[38:39], 0, v[38:39]
	v_lshl_add_u64 v[32:33], s[38:39], 0, v[32:33]
	v_lshl_add_u64 v[34:35], s[38:39], 0, v[34:35]
	s_add_i32 s5, s5, s12
	v_lshl_add_u64 v[0:1], v[0:1], 0, s[14:15]
	v_lshl_add_u64 v[2:3], v[2:3], 0, s[18:19]
	v_lshl_add_u64 v[4:5], v[4:5], 0, s[16:17]
	s_cmpk_gt_i32 s5, 0x3ff
	s_waitcnt vmcnt(0)
	v_cvt_pk_bf16_f32 v56, v6, v7
	v_pk_mul_f32 v[44:45], v[8:9], v[8:9]
	v_pk_mul_f32 v[46:47], v[6:7], v[6:7]
	s_waitcnt vmcnt(2)
	v_pk_mul_f32 v[48:49], v[22:23], v[22:23]
	v_pk_mul_f32 v[50:51], v[20:21], v[20:21]
	v_pk_mov_b32 v[58:59], v[46:47], v[44:45] op_sel:[1,0]
	v_mov_b32_e32 v47, v45
	v_pk_mov_b32 v[44:45], v[50:51], v[48:49] op_sel:[1,0]
	v_mov_b32_e32 v51, v49
	s_waitcnt vmcnt(1)
	v_mul_f32_e32 v55, v24, v24
	s_waitcnt vmcnt(0)
	v_mul_f32_e32 v52, v29, v29
	v_mul_f32_e32 v54, v31, v31
	v_pk_add_f32 v[46:47], v[58:59], v[46:47]
	v_pk_add_f32 v[44:45], v[44:45], v[50:51]
	v_mul_f32_e32 v67, v25, v25
	v_mul_f32_e32 v68, v26, v26
	v_mul_f32_e32 v69, v27, v27
	v_pk_fma_f32 v[48:49], v[28:29], v[28:29], v[52:53] op_sel_hi:[1,1,0]
	v_pk_fma_f32 v[52:53], v[30:31], v[30:31], v[54:55] op_sel_hi:[1,1,0]
	v_pk_add_f32 v[46:47], v[46:47], v[46:47] op_sel:[0,1] op_sel_hi:[1,0]
	v_pk_add_f32 v[44:45], v[44:45], v[44:45] op_sel:[0,1] op_sel_hi:[1,0]
	v_mov_b32_e32 v49, v68
	v_mov_b32_e32 v53, v69
	v_mov_b32_e32 v47, v55
	v_mov_b32_e32 v45, v67
	v_pk_add_f32 v[48:49], v[48:49], v[52:53]
	v_pk_add_f32 v[44:45], v[46:47], v[44:45]
	v_cvt_pk_bf16_f32 v57, v8, v9
	global_store_dwordx2 v[42:43], v[56:57], off
	v_pk_add_f32 v[44:45], v[44:45], v[48:49]
	s_nop 0
	v_add_f32_e32 v44, v44, v45
	s_nop 1
	v_add_f32_dpp v44, v44, v44 quad_perm:[1,0,3,2] row_mask:0xf bank_mask:0xf
	s_nop 1
	v_add_f32_dpp v44, v44, v44 quad_perm:[2,3,0,1] row_mask:0xf bank_mask:0xf
	s_nop 1
	v_add_f32_dpp v44, v44, v44 row_half_mirror row_mask:0xf bank_mask:0xf
	s_nop 1
	v_add_f32_dpp v44, v44, v44 row_mirror row_mask:0xf bank_mask:0xf
	v_mov_b32_e32 v45, v44
	s_nop 1
	v_permlane16_swap_b32_e32 v45, v44
	s_nop 1
	v_add_f32_e32 v44, v44, v45
	v_mov_b32_e32 v45, v44
	s_nop 1
	v_permlane32_swap_b32_e32 v45, v44
	s_nop 1
	v_add_f32_e32 v44, v44, v45
	v_fmamk_f32 v44, v44, 0x3a800000, v226
	v_mul_f32_e32 v45, 0x4b800000, v44
	v_cmp_gt_f32_e32 vcc, s24, v44
	s_nop 1
	v_cndmask_b32_e32 v44, v44, v45, vcc
	v_rsq_f32_e32 v44, v44
	s_nop 0
	v_mul_f32_e32 v45, 0x45800000, v44
	v_cndmask_b32_e32 v44, v44, v45, vcc
	v_mul_f32_e32 v6, v6, v44
	v_mul_f32_e32 v7, v7, v44
	v_mul_f32_e32 v8, v8, v44
	v_mul_f32_e32 v9, v9, v44
	v_cvt_pk_bf16_f32 v6, v6, v7
	v_cvt_pk_bf16_f32 v7, v8, v9
	ds_write_b64 v19, v[6:7]
	v_cvt_pk_bf16_f32 v6, v20, v21
	v_cvt_pk_bf16_f32 v7, v22, v23
	v_mul_f32_e32 v45, v20, v44
	v_mul_f32_e32 v46, v21, v44
	v_mul_f32_e32 v47, v22, v44
	v_mul_f32_e32 v48, v23, v44
	global_store_dwordx2 v[42:43], v[6:7], off offset:512
	v_cvt_pk_bf16_f32 v6, v45, v46
	v_cvt_pk_bf16_f32 v7, v47, v48
	ds_write_b64 v19, v[6:7] offset:512
	v_cvt_pk_bf16_f32 v6, v28, v29
	v_cvt_pk_bf16_f32 v7, v30, v31
	v_mul_f32_e32 v49, v28, v44
	v_mul_f32_e32 v50, v29, v44
	v_mul_f32_e32 v51, v30, v44
	v_mul_f32_e32 v52, v31, v44
	global_store_dwordx2 v[42:43], v[6:7], off offset:1024
	v_cvt_pk_bf16_f32 v6, v49, v50
	v_cvt_pk_bf16_f32 v7, v51, v52
	ds_write_b64 v19, v[6:7] offset:1024
	v_cvt_pk_bf16_f32 v6, v24, v25
	v_cvt_pk_bf16_f32 v7, v26, v27
	v_mul_f32_e32 v53, v24, v44
	v_mul_f32_e32 v54, v25, v44
	v_mul_f32_e32 v55, v26, v44
	v_mul_f32_e32 v56, v27, v44
	global_store_dwordx2 v[42:43], v[6:7], off offset:1536
	v_cvt_pk_bf16_f32 v44, v53, v54
	v_cvt_pk_bf16_f32 v45, v55, v56
	v_mov_b32_e32 v6, v140
	v_mov_b32_e32 v7, v141
	v_mov_b32_e32 v8, v142
	v_mov_b32_e32 v9, v143
	v_mov_b32_e32 v20, v144
	v_mov_b32_e32 v21, v145
	v_mov_b32_e32 v22, v146
	v_mov_b32_e32 v23, v147
	v_mov_b32_e32 v24, v148
	v_mov_b32_e32 v25, v149
	v_mov_b32_e32 v26, v150
	v_mov_b32_e32 v27, v151
	v_mov_b32_e32 v28, v152
	v_mov_b32_e32 v29, v153
	v_mov_b32_e32 v30, v154
	v_mov_b32_e32 v31, v155
	ds_write_b64 v19, v[44:45] offset:1536
	v_add_u32_e32 v53, s0, v18
	s_waitcnt vmcnt(3)
; __device__ __forceinline__ unsigned cvt_pk_bf16(float lo, float hi) { unsigned r; asm volatile("v_cvt_pk_bf16_f32 %0, %1, %2" : "=v"(r) : "v"(lo), "v"(hi)); return r; }
; #define LAS __attribute__((address_space(3)))
; #define LDS_WAIT() asm volatile("s_waitcnt lgkmcnt(0)" ::: "memory")
; template <bool F32SRC> __device__ __forceinline__ void unorm_chunk(LAS unsigned char* lds, const float* xsrc, bf16_t* hbio, bf16_t* Ug, int chunk, const int tid) {
;     ...
;     for (int rr = 0; rr < 2; ++rr) { const int s = 2 * wid + rr; const size_t row = (size_t)chunk * 16 + s;
;         if (F32SRC) { const f32x4* xr = (const f32x4*)(xsrc + row * DM) + lane; f32x4 v[4]; float ss = 0.f;
; #pragma unroll
;             for (int j = 0; j < 4; ++j) { v[j] = __builtin_nontemporal_load(xr + 64 * j); ss += (v[j].x * v[j].x + v[j].y * v[j].y) + (v[j].z * v[j].z + v[j].w * v[j].w); }
;             const float rstd = rsqrtf(wsum_l(ss, lane) * (1.0f / DM) + EPS);
;             u32x2* o = (u32x2*)(hbio + row * DM) + lane;
; #pragma unroll
;             for (int j = 0; j < 4; ++j) { u32x2 w; w.x = pg8::cvt_pk_bf16(v[j].x, v[j].y); w.y = pg8::cvt_pk_bf16(v[j].z, v[j].w); o[64 * j] = w;
;                 u32x2 q; q.x = pg8::cvt_pk_bf16(v[j].x * rstd, v[j].y * rstd); q.y = pg8::cvt_pk_bf16(v[j].z * rstd, v[j].w * rstd); *(LAS u32x2*)(T + s * 2080 + (64 * j + lane) * 8) = q; }
;     ...
;     LDS_WAIT(); __syncthreads();
; #pragma unroll
;     for (int i = 0; i < 4; ++i) { const int gq = 8 * wid + 2 * i + (lane >> 5), l = lane & 31, s = l >> 1, hf = l & 1;
;         const u32x4 q = *(const LAS u32x4*)(T + s * 2080 + gq * 32 + hf * 16);
;         *(u32x4*)(Ug + ((size_t)gq * 1024 + chunk) * 256 + l * 8) = q; }
;     LDS_WAIT(); __syncthreads();
	v_cvt_pk_bf16_f32 v54, v6, v7
	v_pk_mul_f32 v[40:41], v[8:9], v[8:9]
	v_pk_mul_f32 v[44:45], v[6:7], v[6:7]
	s_waitcnt vmcnt(2)
	v_pk_mul_f32 v[46:47], v[22:23], v[22:23]
	v_pk_mul_f32 v[48:49], v[20:21], v[20:21]
	v_pk_mov_b32 v[56:57], v[44:45], v[40:41] op_sel:[1,0]
	v_mov_b32_e32 v45, v41
	v_pk_mov_b32 v[40:41], v[48:49], v[46:47] op_sel:[1,0]
	v_mov_b32_e32 v49, v47
	s_waitcnt vmcnt(1)
	v_mul_f32_e32 v50, v25, v25
	v_mul_f32_e32 v52, v27, v27
	v_pk_add_f32 v[44:45], v[56:57], v[44:45]
	v_pk_add_f32 v[40:41], v[40:41], v[48:49]
	s_waitcnt vmcnt(0)
	v_mul_f32_e32 v19, v28, v28
	v_mul_f32_e32 v58, v29, v29
	v_mul_f32_e32 v59, v30, v30
	v_mul_f32_e32 v67, v31, v31
	v_pk_fma_f32 v[46:47], v[24:25], v[24:25], v[50:51] op_sel_hi:[1,1,0]
	v_pk_fma_f32 v[50:51], v[26:27], v[26:27], v[52:53] op_sel_hi:[1,1,0]
	v_pk_add_f32 v[44:45], v[44:45], v[44:45] op_sel:[0,1] op_sel_hi:[1,0]
	v_pk_add_f32 v[40:41], v[40:41], v[40:41] op_sel:[0,1] op_sel_hi:[1,0]
	v_mov_b32_e32 v47, v59
	v_mov_b32_e32 v51, v67
	v_mov_b32_e32 v45, v19
	v_mov_b32_e32 v41, v58
	v_pk_add_f32 v[46:47], v[46:47], v[50:51]
	v_pk_add_f32 v[40:41], v[44:45], v[40:41]
	v_cvt_pk_bf16_f32 v55, v8, v9
	global_store_dwordx2 v[42:43], v[54:55], off offset:2048
	v_pk_add_f32 v[40:41], v[40:41], v[46:47]
	s_nop 0
	v_add_f32_e32 v19, v40, v41
	s_nop 1
	v_add_f32_dpp v19, v19, v19 quad_perm:[1,0,3,2] row_mask:0xf bank_mask:0xf
	s_nop 1
	v_add_f32_dpp v19, v19, v19 quad_perm:[2,3,0,1] row_mask:0xf bank_mask:0xf
	s_nop 1
	v_add_f32_dpp v19, v19, v19 row_half_mirror row_mask:0xf bank_mask:0xf
	s_nop 1
	v_add_f32_dpp v19, v19, v19 row_mirror row_mask:0xf bank_mask:0xf
	v_mov_b32_e32 v40, v19
	s_nop 1
	v_permlane16_swap_b32_e32 v40, v19
	s_nop 1
	v_add_f32_e32 v19, v19, v40
	v_mov_b32_e32 v40, v19
	s_nop 1
	v_permlane32_swap_b32_e32 v40, v19
	s_nop 1
	v_add_f32_e32 v19, v19, v40
	v_fmamk_f32 v19, v19, 0x3a800000, v226
	v_mul_f32_e32 v40, 0x4b800000, v19
	v_cmp_gt_f32_e32 vcc, s24, v19
	s_nop 1
	v_cndmask_b32_e32 v19, v19, v40, vcc
	v_rsq_f32_e32 v19, v19
	s_nop 0
	v_mul_f32_e32 v40, 0x45800000, v19
	v_cndmask_b32_e32 v19, v19, v40, vcc
	v_mul_f32_e32 v6, v6, v19
	v_mul_f32_e32 v7, v7, v19
	v_mul_f32_e32 v8, v8, v19
	v_mul_f32_e32 v9, v9, v19
	v_cvt_pk_bf16_f32 v6, v6, v7
	v_cvt_pk_bf16_f32 v7, v8, v9
	ds_write_b64 v53, v[6:7]
	v_cvt_pk_bf16_f32 v6, v20, v21
	v_cvt_pk_bf16_f32 v7, v22, v23
	v_mul_f32_e32 v40, v20, v19
	v_mul_f32_e32 v41, v21, v19
	v_mul_f32_e32 v44, v22, v19
	v_mul_f32_e32 v45, v23, v19
	global_store_dwordx2 v[42:43], v[6:7], off offset:2560
	v_cvt_pk_bf16_f32 v6, v40, v41
	v_cvt_pk_bf16_f32 v7, v44, v45
	ds_write_b64 v53, v[6:7] offset:512
	v_cvt_pk_bf16_f32 v6, v24, v25
	v_cvt_pk_bf16_f32 v7, v26, v27
	v_mul_f32_e32 v46, v24, v19
	v_mul_f32_e32 v47, v25, v19
	v_mul_f32_e32 v48, v26, v19
	v_mul_f32_e32 v49, v27, v19
	global_store_dwordx2 v[42:43], v[6:7], off offset:3072
	v_cvt_pk_bf16_f32 v6, v46, v47
	v_cvt_pk_bf16_f32 v7, v48, v49
	ds_write_b64 v53, v[6:7] offset:1024
	v_cvt_pk_bf16_f32 v6, v28, v29
	v_cvt_pk_bf16_f32 v7, v30, v31
	v_mul_f32_e32 v50, v28, v19
	v_mul_f32_e32 v51, v29, v19
	v_mul_f32_e32 v52, v30, v19
	v_mul_f32_e32 v19, v31, v19
	global_store_dwordx2 v[42:43], v[6:7], off offset:3584
	v_cvt_pk_bf16_f32 v6, v50, v51
	v_cvt_pk_bf16_f32 v7, v52, v19
	ds_write_b64 v53, v[6:7] offset:1536
	s_waitcnt lgkmcnt(0)
	s_waitcnt lgkmcnt(0)
	s_barrier
	ds_read_b128 v[6:9], v60
	ds_read_b128 v[20:23], v61
	ds_read_b128 v[24:27], v62
	ds_read_b128 v[28:31], v63
	s_waitcnt lgkmcnt(3)
	global_store_dwordx4 v[36:37], v[6:9], off
	s_waitcnt lgkmcnt(2)
	global_store_dwordx4 v[38:39], v[20:23], off
	s_waitcnt lgkmcnt(1)
	global_store_dwordx4 v[32:33], v[24:27], off
	s_waitcnt lgkmcnt(0)
	global_store_dwordx4 v[34:35], v[28:31], off
	s_waitcnt lgkmcnt(0)
	s_barrier
	s_cbranch_scc0 .LBB0_312
